# grid barrier: cross-XCC arrival counter replicated 16x (leaders add to all, each WG polls its own XCC's replica) on top of best6
# speedup vs baseline: 1.0156x; 1.0104x over previous
.LBB0_58:
	s_or_b64 exec, exec, s[4:5]
	v_cvt_f32_u32_e32 v6, v3
	s_waitcnt vmcnt(0)
	v_readfirstlane_b32 s4, v5
	v_sub_u32_e32 v5, 0, v3
	v_rcp_iflag_f32_e32 v6, v6
	v_add_u32_e32 v7, s4, v4
	v_mul_f32_e32 v6, 0x4f7ffffe, v6
	v_cvt_u32_f32_e32 v6, v6
	v_mul_lo_u32 v4, v5, v6
	v_mul_hi_u32 v4, v6, v4
	v_add_u32_e32 v4, v6, v4
	v_mul_hi_u32 v4, v7, v4
	v_mul_lo_u32 v5, v4, v3
	v_sub_u32_e32 v5, v7, v5
	v_add_u32_e32 v6, 1, v4
	v_cmp_ge_u32_e32 vcc, v5, v3
	s_nop 1
	v_cndmask_b32_e32 v4, v4, v6, vcc
	v_sub_u32_e32 v6, v5, v3
	v_cndmask_b32_e32 v5, v5, v6, vcc
	v_add_u32_e32 v6, 1, v4
	v_cmp_ge_u32_e32 vcc, v5, v3
	v_add_u32_e32 v5, 1, v7
	s_nop 0
	v_cndmask_b32_e32 v4, v4, v6, vcc
	v_add_u32_e32 v4, 1, v4
	v_mul_lo_u32 v3, v4, v3
	v_cmp_eq_u32_e32 vcc, v5, v3
	s_and_saveexec_b64 s[4:5], vcc
	s_cbranch_execz .LBB0_61
	s_mov_b64 s[6:7], exec
	v_mbcnt_lo_u32_b32 v3, s6, 0
	buffer_wbl2 sc1
	s_waitcnt lgkmcnt(0)
	s_waitcnt vmcnt(0)
	v_mbcnt_hi_u32_b32 v3, s7, v3
	v_cmp_eq_u32_e32 vcc, 0, v3
	s_and_b64 s[8:9], exec, vcc
	s_mov_b64 exec, s[8:9]
	s_cbranch_execz .LBB0_61
	s_bcnt1_i32_b64 s8, s[6:7]
	s_getpc_b64 s[6:7]
	s_add_u32 s6, s6, g_ctl@rel32@lo+13316
	s_addc_u32 s7, s7, g_ctl@rel32@hi+13324
	v_mov_b32_e32 v3, 0
	v_mov_b32_e32 v5, s8
	global_atomic_add v3, v5, s[6:7]
	global_atomic_add v3, v5, s[6:7] offset:256
	global_atomic_add v3, v5, s[6:7] offset:512
	global_atomic_add v3, v5, s[6:7] offset:768
	global_atomic_add v3, v5, s[6:7] offset:1024
	global_atomic_add v3, v5, s[6:7] offset:1280
	global_atomic_add v3, v5, s[6:7] offset:1536
	global_atomic_add v3, v5, s[6:7] offset:1792
	global_atomic_add v3, v5, s[6:7] offset:2048
	global_atomic_add v3, v5, s[6:7] offset:2304
	global_atomic_add v3, v5, s[6:7] offset:2560
	global_atomic_add v3, v5, s[6:7] offset:2816
	global_atomic_add v3, v5, s[6:7] offset:3072
	global_atomic_add v3, v5, s[6:7] offset:3328
	global_atomic_add v3, v5, s[6:7] offset:3584
	global_atomic_add v3, v5, s[6:7] offset:3840
.LBB0_61:
	s_or_b64 exec, exec, s[4:5]
	s_waitcnt vmcnt(0)
	buffer_inv sc1
	v_mov_b32_e32 v3, 0
	s_getpc_b64 s[4:5]
	s_add_u32 s4, s4, g_ctl@rel32@lo+13316
	s_addc_u32 s5, s5, g_ctl@rel32@hi+13324
	s_lshl_b32 vcc_lo, s62, 8
	s_add_u32 s4, s4, vcc_lo
	s_addc_u32 s5, s5, 0
	global_load_dword v5, v3, s[4:5] sc1
	s_waitcnt lgkmcnt(0)
	v_mul_lo_u32 v2, v4, v2
	s_waitcnt vmcnt(0)
	v_cmp_lt_u32_e32 vcc, v5, v2
	s_and_saveexec_b64 s[4:5], vcc
	s_cbranch_execz .LBB0_73
	s_mov_b32 s8, 1
	s_mov_b64 s[6:7], 0
	s_branch .LBB0_64

.LBB0_68:
	s_getpc_b64 s[12:13]
	s_add_u32 s12, s12, g_ctl@rel32@lo+13316
	s_addc_u32 s13, s13, g_ctl@rel32@hi+13324
	s_lshl_b32 vcc_lo, s62, 8
	s_add_u32 s12, s12, vcc_lo
	s_addc_u32 s13, s13, 0
	global_load_dword v4, v3, s[12:13] sc1
	s_add_i32 s8, s8, 1
	s_mov_b64 s[18:19], -1
	s_waitcnt vmcnt(0)
	v_cmp_ge_u32_e32 vcc, v4, v2
	s_orn2_b64 s[16:17], vcc, exec
	s_branch .LBB0_63

.LBB0_98:
	s_or_b64 exec, exec, s[2:3]
	v_cvt_f32_u32_e32 v6, v3
	s_waitcnt vmcnt(0)
	v_readfirstlane_b32 s2, v5
	v_sub_u32_e32 v5, 0, v3
	v_rcp_iflag_f32_e32 v6, v6
	v_add_u32_e32 v7, s2, v4
	v_mul_f32_e32 v6, 0x4f7ffffe, v6
	v_cvt_u32_f32_e32 v6, v6
	v_mul_lo_u32 v4, v5, v6
	v_mul_hi_u32 v4, v6, v4
	v_add_u32_e32 v4, v6, v4
	v_mul_hi_u32 v4, v7, v4
	v_mul_lo_u32 v5, v4, v3
	v_sub_u32_e32 v5, v7, v5
	v_add_u32_e32 v6, 1, v4
	v_cmp_ge_u32_e32 vcc, v5, v3
	s_nop 1
	v_cndmask_b32_e32 v4, v4, v6, vcc
	v_sub_u32_e32 v6, v5, v3
	v_cndmask_b32_e32 v5, v5, v6, vcc
	v_add_u32_e32 v6, 1, v4
	v_cmp_ge_u32_e32 vcc, v5, v3
	v_add_u32_e32 v5, 1, v7
	s_nop 0
	v_cndmask_b32_e32 v4, v4, v6, vcc
	v_add_u32_e32 v4, 1, v4
	v_mul_lo_u32 v3, v4, v3
	v_cmp_eq_u32_e32 vcc, v5, v3
	s_and_saveexec_b64 s[2:3], vcc
	s_cbranch_execz .LBB0_101
	s_mov_b64 s[4:5], exec
	v_mbcnt_lo_u32_b32 v3, s4, 0
	buffer_wbl2 sc1
	s_waitcnt lgkmcnt(0)
	s_waitcnt vmcnt(0)
	v_mbcnt_hi_u32_b32 v3, s5, v3
	v_cmp_eq_u32_e32 vcc, 0, v3
	s_and_b64 s[6:7], exec, vcc
	s_mov_b64 exec, s[6:7]
	s_cbranch_execz .LBB0_101
	s_bcnt1_i32_b64 s6, s[4:5]
	s_getpc_b64 s[4:5]
	s_add_u32 s4, s4, g_ctl@rel32@lo+13316
	s_addc_u32 s5, s5, g_ctl@rel32@hi+13324
	v_mov_b32_e32 v3, 0
	v_mov_b32_e32 v5, s6
	global_atomic_add v3, v5, s[4:5]
	global_atomic_add v3, v5, s[4:5] offset:256
	global_atomic_add v3, v5, s[4:5] offset:512
	global_atomic_add v3, v5, s[4:5] offset:768
	global_atomic_add v3, v5, s[4:5] offset:1024
	global_atomic_add v3, v5, s[4:5] offset:1280
	global_atomic_add v3, v5, s[4:5] offset:1536
	global_atomic_add v3, v5, s[4:5] offset:1792
	global_atomic_add v3, v5, s[4:5] offset:2048
	global_atomic_add v3, v5, s[4:5] offset:2304
	global_atomic_add v3, v5, s[4:5] offset:2560
	global_atomic_add v3, v5, s[4:5] offset:2816
	global_atomic_add v3, v5, s[4:5] offset:3072
	global_atomic_add v3, v5, s[4:5] offset:3328
	global_atomic_add v3, v5, s[4:5] offset:3584
	global_atomic_add v3, v5, s[4:5] offset:3840
.LBB0_101:
	s_or_b64 exec, exec, s[2:3]
	s_waitcnt vmcnt(0)
	buffer_inv sc1
	v_mov_b32_e32 v3, 0
	s_getpc_b64 s[2:3]
	s_add_u32 s2, s2, g_ctl@rel32@lo+13316
	s_addc_u32 s3, s3, g_ctl@rel32@hi+13324
	s_lshl_b32 vcc_lo, s62, 8
	s_add_u32 s2, s2, vcc_lo
	s_addc_u32 s3, s3, 0
	global_load_dword v5, v3, s[2:3] sc1
	s_waitcnt lgkmcnt(0)
	v_mul_lo_u32 v2, v4, v2
	s_waitcnt vmcnt(0)
	v_cmp_lt_u32_e32 vcc, v5, v2
	s_and_saveexec_b64 s[2:3], vcc
	s_cbranch_execz .LBB0_113
	s_mov_b32 s8, 1
	s_mov_b64 s[4:5], 0
	s_branch .LBB0_104

.LBB0_108:
	s_getpc_b64 s[12:13]
	s_add_u32 s12, s12, g_ctl@rel32@lo+13316
	s_addc_u32 s13, s13, g_ctl@rel32@hi+13324
	s_lshl_b32 vcc_lo, s62, 8
	s_add_u32 s12, s12, vcc_lo
	s_addc_u32 s13, s13, 0
	global_load_dword v4, v3, s[12:13] sc1
	s_add_i32 s8, s8, 1
	s_mov_b64 s[18:19], -1
	s_waitcnt vmcnt(0)
	v_cmp_ge_u32_e32 vcc, v4, v2
	s_orn2_b64 s[14:15], vcc, exec
	s_branch .LBB0_103

.LBB0_311:
	s_getpc_b64 s[12:13]
	s_add_u32 s12, s12, g_ctl@rel32@lo+13316
	s_addc_u32 s13, s13, g_ctl@rel32@hi+13324
	s_lshl_b32 vcc_lo, s62, 8
	s_add_u32 s12, s12, vcc_lo
	s_addc_u32 s13, s13, 0
	global_load_dword v4, v3, s[12:13] sc1
	s_add_i32 s8, s8, 1
	s_mov_b64 s[14:15], -1
	s_waitcnt vmcnt(0)
	v_cmp_ge_u32_e32 vcc, v4, v2
	s_orn2_b64 s[12:13], vcc, exec
	s_branch .LBB0_306

.LBB0_771:
	s_or_b64 exec, exec, s[2:3]
	v_cvt_f32_u32_e32 v5, v2
	s_waitcnt vmcnt(0)
	v_readfirstlane_b32 s2, v4
	v_sub_u32_e32 v4, 0, v2
	v_rcp_iflag_f32_e32 v5, v5
	v_add_u32_e32 v6, s2, v3
	v_mul_f32_e32 v5, 0x4f7ffffe, v5
	v_cvt_u32_f32_e32 v5, v5
	v_mul_lo_u32 v3, v4, v5
	v_mul_hi_u32 v3, v5, v3
	v_add_u32_e32 v3, v5, v3
	v_mul_hi_u32 v3, v6, v3
	v_mul_lo_u32 v4, v3, v2
	v_sub_u32_e32 v4, v6, v4
	v_add_u32_e32 v5, 1, v3
	v_cmp_ge_u32_e32 vcc, v4, v2
	s_nop 1
	v_cndmask_b32_e32 v3, v3, v5, vcc
	v_sub_u32_e32 v5, v4, v2
	v_cndmask_b32_e32 v4, v4, v5, vcc
	v_add_u32_e32 v5, 1, v3
	v_cmp_ge_u32_e32 vcc, v4, v2
	v_add_u32_e32 v4, 1, v6
	s_nop 0
	v_cndmask_b32_e32 v3, v3, v5, vcc
	v_add_u32_e32 v3, 1, v3
	v_mul_lo_u32 v2, v3, v2
	v_cmp_eq_u32_e32 vcc, v4, v2
	s_and_saveexec_b64 s[2:3], vcc
	s_cbranch_execz .LBB0_774
	s_mov_b64 s[4:5], exec
	v_mbcnt_lo_u32_b32 v2, s4, 0
	buffer_wbl2 sc1
	s_waitcnt lgkmcnt(0)
	s_waitcnt vmcnt(0)
	v_mbcnt_hi_u32_b32 v2, s5, v2
	v_cmp_eq_u32_e32 vcc, 0, v2
	s_and_b64 s[6:7], exec, vcc
	s_mov_b64 exec, s[6:7]
	s_cbranch_execz .LBB0_774
	s_bcnt1_i32_b64 s6, s[4:5]
	s_getpc_b64 s[4:5]
	s_add_u32 s4, s4, g_ctl@rel32@lo+13316
	s_addc_u32 s5, s5, g_ctl@rel32@hi+13324
	v_mov_b32_e32 v2, 0
	v_mov_b32_e32 v4, s6
	global_atomic_add v2, v4, s[4:5]
	global_atomic_add v2, v4, s[4:5] offset:256
	global_atomic_add v2, v4, s[4:5] offset:512
	global_atomic_add v2, v4, s[4:5] offset:768
	global_atomic_add v2, v4, s[4:5] offset:1024
	global_atomic_add v2, v4, s[4:5] offset:1280
	global_atomic_add v2, v4, s[4:5] offset:1536
	global_atomic_add v2, v4, s[4:5] offset:1792
	global_atomic_add v2, v4, s[4:5] offset:2048
	global_atomic_add v2, v4, s[4:5] offset:2304
	global_atomic_add v2, v4, s[4:5] offset:2560
	global_atomic_add v2, v4, s[4:5] offset:2816
	global_atomic_add v2, v4, s[4:5] offset:3072
	global_atomic_add v2, v4, s[4:5] offset:3328
	global_atomic_add v2, v4, s[4:5] offset:3584
	global_atomic_add v2, v4, s[4:5] offset:3840
.LBB0_774:
	s_or_b64 exec, exec, s[2:3]
	s_waitcnt vmcnt(0)
	buffer_inv sc1
	v_mov_b32_e32 v2, 0
	s_getpc_b64 s[2:3]
	s_add_u32 s2, s2, g_ctl@rel32@lo+13316
	s_addc_u32 s3, s3, g_ctl@rel32@hi+13324
	s_lshl_b32 vcc_lo, s62, 8
	s_add_u32 s2, s2, vcc_lo
	s_addc_u32 s3, s3, 0
	global_load_dword v4, v2, s[2:3] sc1
	s_waitcnt lgkmcnt(0)
	v_mul_lo_u32 v1, v3, v1
	s_waitcnt vmcnt(0)
	v_cmp_lt_u32_e32 vcc, v4, v1
	s_and_saveexec_b64 s[2:3], vcc
	s_cbranch_execz .LBB0_786
	s_mov_b32 s8, 1
	s_mov_b64 s[4:5], 0
	s_branch .LBB0_777

.LBB0_781:
	s_getpc_b64 s[10:11]
	s_add_u32 s10, s10, g_ctl@rel32@lo+13316
	s_addc_u32 s11, s11, g_ctl@rel32@hi+13324
	s_lshl_b32 vcc_lo, s62, 8
	s_add_u32 s10, s10, vcc_lo
	s_addc_u32 s11, s11, 0
	global_load_dword v3, v2, s[10:11] sc1
	s_add_i32 s8, s8, 1
	s_mov_b64 s[12:13], -1
	s_waitcnt vmcnt(0)
	v_cmp_ge_u32_e32 vcc, v3, v1
	s_orn2_b64 s[10:11], vcc, exec
	s_branch .LBB0_776
